# hgrn chunk loop: LDS operand reads of the PV/QS'/S-update MFMA sections software-pipelined (counted lgkmcnt, rotating temp registers)
# speedup vs baseline: 1.0104x; 1.0004x over previous
; __device__ __forceinline__ void item_hgrn(const Params& p, int l, int sidx) {
;     ...
; #pragma unroll
;         for (int j = 0; j < 4; ++j) {
;           int trow = tt * 16 + fq * 4 + j, scol = st * 16 + fr;
;           float v = (scol <= trow) ? pa[j] : 0.f;
;           Ps[trow * 72 + scol] = f2bf(v);
;         }
;       }
;     }
;     __syncthreads();
;     f32x4 oacc[4];
;     const int tt = wid & 3, dvh = wid >> 2;
;     {
; #pragma unroll
;       for (int n = 0; n < 4; ++n) oacc[n] = f32x4{0.f, 0.f, 0.f, 0.f};
; #pragma unroll
;       for (int ks = 0; ks < 2; ++ks) {
;         bf16x8 a = *reinterpret_cast<const bf16x8*>(Ps + (tt * 16 + fr) * 72 + ks * 32 + fq * 8);
; #pragma unroll
;         for (int n = 0; n < 4; ++n) {
;           bf16x8 bb = *reinterpret_cast<const bf16x8*>(VTs + (dvh * 64 + n * 16 + fr) * 72 + ks * 32 + fq * 8);
;           oacc[n] = __builtin_amdgcn_mfma_f32_16x16x32_bf16(a, bb, oacc[n], 0, 0, 0);
;         }
;       }
; #pragma unroll
;       for (int ks = 0; ks < 4; ++ks) {
;         bf16x8 a = *reinterpret_cast<const bf16x8*>(Qs + (tt * 16 + fr) * 136 + ks * 32 + fq * 8);
; #pragma unroll
;         for (int n = 0; n < 4; ++n) {
;           bf16x8 bb = *reinterpret_cast<const bf16x8*>(SpT + (dvh * 64 + n * 16 + fr) * 136 + ks * 32 + fq * 8);
;           oacc[n] = __builtin_amdgcn_mfma_f32_16x16x32_bf16(a, bb, oacc[n], 0, 0, 0);
;         }
;       }
.LBB0_816:
	s_nop 7
	v_cndmask_b32_e64 v40, v40, 0, s[20:21]
	v_bfe_u32 v44, v40, 16, 1
	v_add3_u32 v40, v40, v44, s80
	ds_write_b16_d16_hi v149, v40
	v_cndmask_b32_e64 v40, v41, 0, s[22:23]
	v_bfe_u32 v41, v40, 16, 1
	v_add3_u32 v40, v40, v41, s80
	ds_write_b16_d16_hi v150, v40
	v_cndmask_b32_e64 v40, v42, 0, s[24:25]
	v_bfe_u32 v41, v40, 16, 1
	v_add3_u32 v40, v40, v41, s80
	ds_write_b16_d16_hi v151, v40
	v_cndmask_b32_e64 v40, v43, 0, s[26:27]
	v_bfe_u32 v41, v40, 16, 1
	v_add3_u32 v40, v40, v41, s80
	ds_write_b16_d16_hi v152, v40
	s_waitcnt lgkmcnt(0)
	s_barrier
	ds_read_b128 v[40:43], v83
	ds_read_b128 v[44:47], v166 offset:53248
	ds_read_b128 v[48:51], v239 offset:55552
	ds_read_b128 v[52:55], v166 offset:57920
	ds_read_b128 v[56:59], v239 offset:60224
	ds_read_b128 v[234:237], v83 offset:64
	ds_read_b128 v[218:221], v166 offset:53312
	ds_read_b128 v[222:225], v239 offset:55616
	ds_read_b128 v[226:229], v166 offset:57856
	s_waitcnt lgkmcnt(7)
	v_mfma_f32_16x16x32_bf16 v[44:47], v[40:43], v[44:47], 0
	s_waitcnt lgkmcnt(6)
	v_mfma_f32_16x16x32_bf16 v[48:51], v[40:43], v[48:51], 0
	s_waitcnt lgkmcnt(5)
	v_mfma_f32_16x16x32_bf16 v[52:55], v[40:43], v[52:55], 0
	s_waitcnt lgkmcnt(4)
	v_mfma_f32_16x16x32_bf16 v[40:43], v[40:43], v[56:59], 0
	ds_read_b128 v[230:233], v239 offset:60160
	s_waitcnt lgkmcnt(3)
	v_mfma_f32_16x16x32_bf16 v[44:47], v[234:237], v[218:221], v[44:47]
	ds_read_b128 v[240:243], v101
	ds_read_b128 v[218:221], v167
	s_waitcnt lgkmcnt(4)
	v_mfma_f32_16x16x32_bf16 v[48:51], v[234:237], v[222:225], v[48:51]
	ds_read_b128 v[222:225], v167 offset:4352
	s_waitcnt lgkmcnt(4)
	v_mfma_f32_16x16x32_bf16 v[52:55], v[234:237], v[226:229], v[52:55]
	ds_read_b128 v[226:229], v167 offset:8704
	s_waitcnt lgkmcnt(4)
	v_mfma_f32_16x16x32_bf16 v[40:43], v[234:237], v[230:233], v[40:43]
	ds_read_b128 v[230:233], v167 offset:13056
	s_waitcnt lgkmcnt(3)
	v_mfma_f32_16x16x32_bf16 v[44:47], v[240:243], v[218:221], v[44:47]
	ds_read_b128 v[234:237], v101 offset:64
	ds_read_b128 v[218:221], v167 offset:64
	s_waitcnt lgkmcnt(4)
	v_mfma_f32_16x16x32_bf16 v[48:51], v[240:243], v[222:225], v[48:51]
	ds_read_b128 v[222:225], v167 offset:4416
	s_waitcnt lgkmcnt(4)
	v_mfma_f32_16x16x32_bf16 v[52:55], v[240:243], v[226:229], v[52:55]
	ds_read_b128 v[226:229], v167 offset:8768
	s_waitcnt lgkmcnt(4)
	v_mfma_f32_16x16x32_bf16 v[40:43], v[240:243], v[230:233], v[40:43]
	ds_read_b128 v[230:233], v167 offset:13120
	s_waitcnt lgkmcnt(3)
	v_mfma_f32_16x16x32_bf16 v[44:47], v[234:237], v[218:221], v[44:47]
	ds_read_b128 v[240:243], v101 offset:128
	ds_read_b128 v[218:221], v167 offset:128
	s_waitcnt lgkmcnt(4)
	v_mfma_f32_16x16x32_bf16 v[48:51], v[234:237], v[222:225], v[48:51]
	ds_read_b128 v[222:225], v167 offset:4480
	s_waitcnt lgkmcnt(4)
	v_mfma_f32_16x16x32_bf16 v[52:55], v[234:237], v[226:229], v[52:55]
	ds_read_b128 v[226:229], v167 offset:8832
	s_waitcnt lgkmcnt(4)
	v_mfma_f32_16x16x32_bf16 v[40:43], v[234:237], v[230:233], v[40:43]
	ds_read_b128 v[230:233], v167 offset:13184
	s_waitcnt lgkmcnt(3)
	v_mfma_f32_16x16x32_bf16 v[44:47], v[240:243], v[218:221], v[44:47]
	ds_read_b128 v[234:237], v101 offset:192
	ds_read_b128 v[218:221], v167 offset:192
	s_waitcnt lgkmcnt(4)
	v_mfma_f32_16x16x32_bf16 v[48:51], v[240:243], v[222:225], v[48:51]
	ds_read_b128 v[222:225], v167 offset:4544
	s_waitcnt lgkmcnt(4)
	v_mfma_f32_16x16x32_bf16 v[52:55], v[240:243], v[226:229], v[52:55]
	ds_read_b128 v[226:229], v167 offset:8896
	s_waitcnt lgkmcnt(4)
	v_mfma_f32_16x16x32_bf16 v[56:59], v[240:243], v[230:233], v[40:43]
	ds_read_b128 v[230:233], v167 offset:13248
	s_waitcnt lgkmcnt(3)
	v_mfma_f32_16x16x32_bf16 v[40:43], v[234:237], v[218:221], v[44:47]
	s_waitcnt lgkmcnt(2)
	v_mfma_f32_16x16x32_bf16 v[44:47], v[234:237], v[222:225], v[48:51]
	s_waitcnt lgkmcnt(1)
	v_mfma_f32_16x16x32_bf16 v[48:51], v[234:237], v[226:229], v[52:55]
	s_waitcnt lgkmcnt(0)
; __device__ __forceinline__ void item_hgrn(const Params& p, int l, int sidx) {
;     ...
; #pragma unroll
;       for (int ks = 0; ks < 4; ++ks) {
;         bf16x8 a = *reinterpret_cast<const bf16x8*>(Qs + (tt * 16 + fr) * 136 + ks * 32 + fq * 8);
; #pragma unroll
;         for (int n = 0; n < 4; ++n) {
;           bf16x8 bb = *reinterpret_cast<const bf16x8*>(SpT + (dvh * 64 + n * 16 + fr) * 136 + ks * 32 + fq * 8);
;           oacc[n] = __builtin_amdgcn_mfma_f32_16x16x32_bf16(a, bb, oacc[n], 0, 0, 0);
;         }
;       }
; #pragma unroll
;       for (int j = 0; j < 4; ++j) {
;         float ss = 0.f;
; #pragma unroll
;         for (int n = 0; n < 4; ++n) ss += oacc[n][j] * oacc[n][j];
;         ss += __shfl_xor(ss, 1); ss += __shfl_xor(ss, 2); ss += __shfl_xor(ss, 4); ss += __shfl_xor(ss, 8);
;         if (fr == 0) ssq[dvh * 64 + tt * 16 + fq * 4 + j] = ss;
;       }
;     }
;     {
; #pragma unroll
;       for (int ks = 0; ks < 2; ++ks) {
;         bf16x8 a = *reinterpret_cast<const bf16x8*>(KTs + (16 * wid + fr) * 72 + ks * 32 + fq * 8);
; #pragma unroll
;         for (int n = 0; n < 8; ++n) {
;           bf16x8 bb = *reinterpret_cast<const bf16x8*>(VTs + (n * 16 + fr) * 72 + ks * 32 + fq * 8);
;           S[n] = __builtin_amdgcn_mfma_f32_16x16x32_bf16(a, bb, S[n], 0, 0, 0);
;         }
;       }
	v_mfma_f32_16x16x32_bf16 v[52:55], v[234:237], v[230:233], v[56:59]
	ds_read_b128 v[234:237], v168 offset:53248
	ds_read_b128 v[240:243], v169 offset:53248
	ds_read_b128 v[218:221], v170 offset:53312
	ds_read_b128 v[222:225], v171 offset:53312
	ds_read_b128 v[230:233], v84 offset:34880
	s_nop 2
	v_mul_f32_e32 v56, v44, v44
	v_mul_f32_e32 v57, v45, v45
	v_mul_f32_e32 v58, v46, v46
	v_mul_f32_e32 v59, v47, v47
	v_fmac_f32_e32 v56, v40, v40
	v_fmac_f32_e32 v57, v41, v41
	v_fmac_f32_e32 v58, v42, v42
	v_fmac_f32_e32 v59, v43, v43
	v_fmac_f32_e32 v56, v48, v48
	v_fmac_f32_e32 v57, v49, v49
	v_fmac_f32_e32 v58, v50, v50
	v_fmac_f32_e32 v59, v51, v51
	v_fmac_f32_e32 v56, v52, v52
	v_fmac_f32_e32 v57, v53, v53
	v_fmac_f32_e32 v58, v54, v54
	v_fmac_f32_e32 v59, v55, v55
	v_add_f32_dpp v56, v56, v56 quad_perm:[1,0,3,2] row_mask:0xf bank_mask:0xf
	v_add_f32_dpp v57, v57, v57 quad_perm:[1,0,3,2] row_mask:0xf bank_mask:0xf
	v_add_f32_dpp v58, v58, v58 quad_perm:[1,0,3,2] row_mask:0xf bank_mask:0xf
	v_add_f32_dpp v59, v59, v59 quad_perm:[1,0,3,2] row_mask:0xf bank_mask:0xf
	v_add_f32_dpp v56, v56, v56 quad_perm:[2,3,0,1] row_mask:0xf bank_mask:0xf
	v_add_f32_dpp v57, v57, v57 quad_perm:[2,3,0,1] row_mask:0xf bank_mask:0xf
	v_add_f32_dpp v58, v58, v58 quad_perm:[2,3,0,1] row_mask:0xf bank_mask:0xf
	v_add_f32_dpp v59, v59, v59 quad_perm:[2,3,0,1] row_mask:0xf bank_mask:0xf
	v_add_f32_dpp v56, v56, v56 row_half_mirror row_mask:0xf bank_mask:0xf
	v_add_f32_dpp v57, v57, v57 row_half_mirror row_mask:0xf bank_mask:0xf
	v_add_f32_dpp v58, v58, v58 row_half_mirror row_mask:0xf bank_mask:0xf
	v_add_f32_dpp v59, v59, v59 row_half_mirror row_mask:0xf bank_mask:0xf
	v_add_f32_dpp v56, v56, v56 row_mirror row_mask:0xf bank_mask:0xf
	v_add_f32_dpp v57, v57, v57 row_mirror row_mask:0xf bank_mask:0xf
	v_add_f32_dpp v58, v58, v58 row_mirror row_mask:0xf bank_mask:0xf
	v_add_f32_dpp v59, v59, v59 row_mirror row_mask:0xf bank_mask:0xf
	v_add_u32_e32 v207, s87, v96
	s_and_saveexec_b64 s[2:3], s[10:11]
	ds_write_b128 v207, v[56:59]
	s_or_b64 exec, exec, s[2:3]
	s_waitcnt lgkmcnt(0)
	ds_read_b128 v[56:59], v84 offset:34816
	ds_read_b128 v[226:229], v172 offset:53248
	v_cmp_gt_u32_e32 vcc, s86, v206
	s_waitcnt lgkmcnt(1)
	v_mfma_f32_16x16x32_bf16 v[8:11], v[56:59], v[234:237], v[8:11]
	ds_read_b128 v[234:237], v173 offset:53248
	v_mfma_f32_16x16x32_bf16 v[12:15], v[56:59], v[240:243], v[12:15]
	ds_read_b128 v[240:243], v174 offset:53312
	v_mfma_f32_16x16x32_bf16 v[16:19], v[56:59], v[218:221], v[16:19]
	v_mfma_f32_16x16x32_bf16 v[20:23], v[56:59], v[222:225], v[20:23]
	s_waitcnt lgkmcnt(2)
	v_mfma_f32_16x16x32_bf16 v[218:221], v[56:59], v[226:229], v[24:27]
	s_waitcnt lgkmcnt(1)
	v_mfma_f32_16x16x32_bf16 v[222:225], v[56:59], v[234:237], v[28:31]
	ds_read_b128 v[234:237], v168 offset:53312
	ds_read_b128 v[24:27], v175 offset:53312
	s_waitcnt lgkmcnt(2)
	v_mfma_f32_16x16x32_bf16 v[226:229], v[56:59], v[240:243], v[32:35]
	ds_read_b128 v[240:243], v169 offset:53312
	ds_read_b128 v[28:31], v170 offset:53248
	s_waitcnt lgkmcnt(2)
	v_mfma_f32_16x16x32_bf16 v[36:39], v[56:59], v[24:27], v[36:39]
	ds_read_b128 v[56:59], v174 offset:53248
	ds_read_b128 v[32:35], v171 offset:53248
	v_mfma_f32_16x16x32_bf16 v[8:11], v[230:233], v[234:237], v[8:11]
	ds_read_b128 v[234:237], v172 offset:53312
	s_waitcnt lgkmcnt(4)
	v_mfma_f32_16x16x32_bf16 v[12:15], v[230:233], v[240:243], v[12:15]
	ds_read_b128 v[240:243], v173 offset:53312
	s_waitcnt lgkmcnt(4)
	v_mfma_f32_16x16x32_bf16 v[16:19], v[230:233], v[28:31], v[16:19]
	s_waitcnt lgkmcnt(2)
	v_mfma_f32_16x16x32_bf16 v[24:27], v[230:233], v[32:35], v[20:23]
	s_waitcnt lgkmcnt(1)
	v_mfma_f32_16x16x32_bf16 v[28:31], v[230:233], v[234:237], v[218:221]
	s_nop 0
	ds_read_b128 v[20:23], v175 offset:53248
	s_waitcnt lgkmcnt(1)
	v_mfma_f32_16x16x32_bf16 v[32:35], v[230:233], v[240:243], v[222:225]
	v_mfma_f32_16x16x32_bf16 v[56:59], v[230:233], v[56:59], v[226:229]
	s_waitcnt lgkmcnt(0)
	v_mfma_f32_16x16x32_bf16 v[20:23], v[230:233], v[20:23], v[36:39]
	s_nop 2
	v_add_u32_e32 v36, s88, v96
	ds_read_b128 v[36:39], v36
	s_waitcnt lgkmcnt(0)
	s_barrier
	s_and_saveexec_b64 s[28:29], vcc
	s_cbranch_execnz .LBB0_828
	s_or_b64 exec, exec, s[28:29]
	v_cmp_gt_u32_e32 vcc, s86, v201
	s_and_saveexec_b64 s[28:29], vcc
	s_cbranch_execnz .LBB0_829
